# v5 + nt hint on streaming f32 epilogue traffic (x loads/out stores in phase 6, out loads/stores in phase 10) to keep bf16 intermediates resident in the infinity cache
# baseline (speedup 1.0000x reference)
; __device__ __forceinline__ unsigned cvt_pk_bf16(float lo, float hi) { unsigned r; asm volatile("v_cvt_pk_bf16_f32 %0, %1, %2" : "=v"(r) : "v"(lo), "v"(hi)); return r; }
;     __device__ __forceinline__ void operator()(const f32x4 (&acc)[2][2][4][2], const Unit& u, int wr, int wc, int fr, int fq) const {
;         const int row0 = u.pm * BM + wr * 64 + fr, col0 = u.pn * BM + wc * 32 + 8 * fq;
;         f32x4 gv[2][2];
; #pragma unroll
;         for (int bj = 0; bj < 2; ++bj)
; #pragma unroll
;             for (int n = 0; n < 2; ++n) gv[bj][n] = *(const f32x4*)(g + col0 + bj * HALF + 4 * n);
; #pragma unroll
;         for (int ai = 0; ai < 2; ++ai)
; #pragma unroll
;             for (int m = 0; m < 4; ++m) { const int row = row0 + ai * HALF + m * 16; const size_t off = (size_t)row * ldc + col0;
;                 f32x4 x[2][2]; float s = 0.f;
; #pragma unroll
;                 for (int bj = 0; bj < 2; ++bj)
; #pragma unroll
;                     for (int n = 0; n < 2; ++n) x[bj][n] = *(const f32x4*)(base + off + bj * HALF + 4 * n);
; #pragma unroll
;                 for (int bj = 0; bj < 2; ++bj) {
; #pragma unroll
;                     for (int n = 0; n < 2; ++n) { x[bj][n] = x[bj][n] + acc[ai][bj][m][n]; *(f32x4*)(out + off + bj * HALF + 4 * n) = x[bj][n];
;                         s += (x[bj][n][0] * x[bj][n][0] + x[bj][n][1] * x[bj][n][1]) + (x[bj][n][2] * x[bj][n][2] + x[bj][n][3] * x[bj][n][3]); }
;                     const f32x4 h0 = x[bj][0] * gv[bj][0], h1 = x[bj][1] * gv[bj][1];
;                     u32x4 w; w.x = cvt_pk_bf16(h0[0], h0[1]); w.y = cvt_pk_bf16(h0[2], h0[3]); w.z = cvt_pk_bf16(h1[0], h1[1]); w.w = cvt_pk_bf16(h1[2], h1[3]);
;                     *(u32x4*)(H + off + bj * HALF) = w; }
;                 s += __shfl_xor(s, 16); s += __shfl_xor(s, 32);
;                 if (fq == 0) atomicAdd(ss + row, s);
;                 if (m & 1) asm volatile("" ::: "memory"); }
;     }
.LBB0_848:
	v_lshl_add_u32 v162, s36, 8, v164
	v_lshl_or_b32 v160, s38, 8, v166
	v_ashrrev_i32_e32 v163, 31, v162
	v_ashrrev_i32_e32 v161, 31, v160
	v_lshlrev_b64 v[64:65], 11, v[162:163]
	v_lshl_add_u64 v[188:189], v[64:65], 0, v[160:161]
	v_lshlrev_b64 v[190:191], 2, v[188:189]
	v_lshl_add_u64 v[64:65], s[16:17], 0, v[190:191]
	global_load_dwordx4 v[172:175], v[64:65], off nt
	global_load_dwordx4 v[176:179], v[64:65], off offset:16 nt
	global_load_dwordx4 v[180:183], v[64:65], off offset:512 nt
	global_load_dwordx4 v[184:187], v[64:65], off offset:528 nt
	v_lshl_add_u64 v[64:65], v[160:161], 2, s[14:15]
	global_load_dwordx4 v[76:79], v[64:65], off nt
	global_load_dwordx4 v[72:75], v[64:65], off offset:16 nt
	global_load_dwordx4 v[68:71], v[64:65], off offset:512 nt
	s_nop 0
	global_load_dwordx4 v[64:67], v[64:65], off offset:528 nt
	v_and_b32_e32 v192, 64, v170
	v_xor_b32_e32 v171, 16, v170
	v_add_u32_e32 v192, 64, v192
	v_xor_b32_e32 v193, 32, v170
	v_cmp_lt_i32_e32 vcc, v171, v192
	v_lshl_add_u64 v[190:191], s[8:9], 0, v[190:191]
	v_lshl_add_u64 v[188:189], v[188:189], 1, s[20:21]
	v_cndmask_b32_e32 v171, v170, v171, vcc
	v_cmp_lt_i32_e32 vcc, v193, v192
	v_lshlrev_b32_e32 v171, 2, v171
	s_waitcnt vmcnt(0)
	v_pk_add_f32 v[142:143], v[142:143], v[174:175]
	v_pk_add_f32 v[140:141], v[140:141], v[172:173]
	v_pk_add_f32 v[138:139], v[138:139], v[178:179]
	v_pk_add_f32 v[136:137], v[136:137], v[176:177]
	v_cndmask_b32_e32 v192, v170, v193, vcc
	v_pk_add_f32 v[134:135], v[134:135], v[182:183]
	v_pk_add_f32 v[132:133], v[132:133], v[180:181]
	v_mul_f32_e32 v193, v141, v141
	v_mul_f32_e32 v194, v143, v143
	v_mul_f32_e32 v195, v137, v137
	v_mul_f32_e32 v196, v139, v139
	v_pk_add_f32 v[130:131], v[130:131], v[186:187]
	v_pk_add_f32 v[128:129], v[128:129], v[184:185]
	global_store_dwordx4 v[190:191], v[140:143], off nt
	v_pk_mul_f32 v[172:173], v[78:79], v[142:143]
	v_pk_mul_f32 v[174:175], v[76:77], v[140:141]
	v_mul_f32_e32 v141, v133, v133
	v_mul_f32_e32 v143, v135, v135
	v_fmac_f32_e32 v193, v140, v140
	v_fmac_f32_e32 v194, v142, v142
	v_fmac_f32_e32 v195, v136, v136
	v_fmac_f32_e32 v196, v138, v138
	v_mul_f32_e32 v197, v129, v129
	v_mul_f32_e32 v198, v131, v131
	v_fmac_f32_e32 v141, v132, v132
	v_fmac_f32_e32 v143, v134, v134
	v_add_f32_e32 v140, v193, v194
	v_add_f32_e32 v142, v195, v196
	v_fmac_f32_e32 v197, v128, v128
	v_fmac_f32_e32 v198, v130, v130
	v_add_f32_e32 v141, v141, v143
	v_add_f32_e32 v140, v140, v142
	v_add_f32_e32 v143, v197, v198
	v_add_f32_e32 v140, v140, v141
	v_add_f32_e32 v140, v140, v143
	ds_bpermute_b32 v141, v171, v140
	global_store_dwordx4 v[190:191], v[136:139], off offset:16 nt
	v_pk_mul_f32 v[176:177], v[74:75], v[138:139]
	v_pk_mul_f32 v[178:179], v[72:73], v[136:137]
	v_cvt_pk_bf16_f32 v136, v174, v175
	v_cvt_pk_bf16_f32 v137, v172, v173
	v_pk_mul_f32 v[184:185], v[66:67], v[130:131]
	v_cvt_pk_bf16_f32 v138, v178, v179
	v_cvt_pk_bf16_f32 v139, v176, v177
	v_pk_mul_f32 v[186:187], v[64:65], v[128:129]
	global_store_dwordx4 v[188:189], v[136:139], off
	global_store_dwordx4 v[190:191], v[132:135], off offset:512 nt
	global_store_dwordx4 v[190:191], v[128:131], off offset:528 nt
	v_pk_mul_f32 v[180:181], v[70:71], v[134:135]
	v_pk_mul_f32 v[182:183], v[68:69], v[132:133]
	s_waitcnt lgkmcnt(0)
	v_add_f32_e32 v128, v140, v141
	v_lshlrev_b32_e32 v130, 2, v192
	ds_bpermute_b32 v129, v130, v128
	v_cvt_pk_bf16_f32 v132, v182, v183
	v_cvt_pk_bf16_f32 v133, v180, v181
	v_cvt_pk_bf16_f32 v134, v186, v187
	v_cvt_pk_bf16_f32 v135, v184, v185
	global_store_dwordx4 v[188:189], v[132:135], off offset:256
	s_and_saveexec_b64 s[0:1], s[4:5]
	s_cbranch_execz .LBB0_850
	s_waitcnt lgkmcnt(0)
	v_add_f32_e32 v131, v128, v129
	v_lshl_add_u64 v[128:129], v[162:163], 2, s[10:11]
	global_atomic_add_f32 v[128:129], v131, off
.LBB0_850:
	s_or_b64 exec, exec, s[0:1]
	v_or_b32_e32 v128, 16, v162
	s_waitcnt lgkmcnt(0)
	v_ashrrev_i32_e32 v129, 31, v128
	v_lshlrev_b64 v[132:133], 11, v[128:129]
	v_lshl_add_u64 v[176:177], v[132:133], 0, v[160:161]
	v_lshlrev_b64 v[178:179], 2, v[176:177]
	v_lshl_add_u64 v[172:173], s[16:17], 0, v[178:179]
	global_load_dwordx4 v[132:135], v[172:173], off nt
	global_load_dwordx4 v[136:139], v[172:173], off offset:16 nt
	global_load_dwordx4 v[140:143], v[172:173], off offset:512 nt
	s_nop 0
	global_load_dwordx4 v[172:175], v[172:173], off offset:528 nt
	v_lshl_add_u64 v[178:179], s[8:9], 0, v[178:179]
	v_lshl_add_u64 v[176:177], v[176:177], 1, s[20:21]
	s_waitcnt vmcnt(3)
	v_pk_add_f32 v[126:127], v[126:127], v[134:135]
	v_pk_add_f32 v[124:125], v[124:125], v[132:133]
	s_waitcnt vmcnt(2)
	v_pk_add_f32 v[122:123], v[122:123], v[138:139]
	v_pk_add_f32 v[120:121], v[120:121], v[136:137]
	s_waitcnt vmcnt(1)
	v_pk_add_f32 v[118:119], v[118:119], v[142:143]
	v_pk_add_f32 v[116:117], v[116:117], v[140:141]
	v_mul_f32_e32 v131, v125, v125
	v_mul_f32_e32 v140, v127, v127
	v_mul_f32_e32 v141, v121, v121
	v_mul_f32_e32 v142, v123, v123
	s_waitcnt vmcnt(0)
	v_pk_add_f32 v[114:115], v[114:115], v[174:175]
	v_pk_add_f32 v[112:113], v[112:113], v[172:173]
	global_store_dwordx4 v[178:179], v[124:127], off nt
	v_pk_mul_f32 v[132:133], v[78:79], v[126:127]
	v_pk_mul_f32 v[134:135], v[76:77], v[124:125]
	v_mul_f32_e32 v125, v117, v117
	v_mul_f32_e32 v127, v119, v119
	v_fmac_f32_e32 v131, v124, v124
	v_fmac_f32_e32 v140, v126, v126
	v_fmac_f32_e32 v141, v120, v120
	v_fmac_f32_e32 v142, v122, v122
	global_store_dwordx4 v[178:179], v[120:123], off offset:16 nt
	v_pk_mul_f32 v[136:137], v[74:75], v[122:123]
	v_pk_mul_f32 v[138:139], v[72:73], v[120:121]
	v_mul_f32_e32 v143, v113, v113
	v_mul_f32_e32 v163, v115, v115
	v_cvt_pk_bf16_f32 v120, v134, v135
	v_cvt_pk_bf16_f32 v121, v132, v133
	v_cvt_pk_bf16_f32 v122, v138, v139
	v_cvt_pk_bf16_f32 v123, v136, v137
	v_fmac_f32_e32 v125, v116, v116
	v_fmac_f32_e32 v127, v118, v118
	v_add_f32_e32 v124, v131, v140
	v_add_f32_e32 v126, v141, v142
	v_fmac_f32_e32 v143, v112, v112
	v_fmac_f32_e32 v163, v114, v114
	global_store_dwordx4 v[176:177], v[120:123], off
	global_store_dwordx4 v[178:179], v[116:119], off offset:512 nt
	global_store_dwordx4 v[178:179], v[112:115], off offset:528 nt
	v_add_f32_e32 v120, v125, v127
	v_add_f32_e32 v122, v124, v126
	v_add_f32_e32 v121, v143, v163
	v_add_f32_e32 v120, v122, v120
	v_add_f32_e32 v124, v120, v121
	ds_bpermute_b32 v125, v171, v124
	v_pk_mul_f32 v[122:123], v[64:65], v[112:113]
	v_pk_mul_f32 v[116:117], v[68:69], v[116:117]
	v_pk_mul_f32 v[118:119], v[70:71], v[118:119]
	v_pk_mul_f32 v[120:121], v[66:67], v[114:115]
	s_waitcnt lgkmcnt(0)
	v_add_f32_e32 v112, v124, v125
	ds_bpermute_b32 v113, v130, v112
	v_cvt_pk_bf16_f32 v114, v116, v117
	v_cvt_pk_bf16_f32 v115, v118, v119
	v_cvt_pk_bf16_f32 v116, v122, v123
	v_cvt_pk_bf16_f32 v117, v120, v121
	global_store_dwordx4 v[176:177], v[114:117], off offset:256
	s_and_saveexec_b64 s[0:1], s[4:5]
	s_cbranch_execz .LBB0_852
	s_waitcnt lgkmcnt(0)
	v_add_f32_e32 v114, v112, v113
	v_lshl_add_u64 v[112:113], v[128:129], 2, s[10:11]
	global_atomic_add_f32 v[112:113], v114, off
; __device__ __forceinline__ unsigned cvt_pk_bf16(float lo, float hi) { unsigned r; asm volatile("v_cvt_pk_bf16_f32 %0, %1, %2" : "=v"(r) : "v"(lo), "v"(hi)); return r; }
;     __device__ __forceinline__ void operator()(const f32x4 (&acc)[2][2][4][2], const Unit& u, int wr, int wc, int fr, int fq) const {
;     ...
;             for (int m = 0; m < 4; ++m) { const int row = row0 + ai * HALF + m * 16; const size_t off = (size_t)row * ldc + col0;
;                 f32x4 x[2][2]; float s = 0.f;
; #pragma unroll
;                 for (int bj = 0; bj < 2; ++bj)
; #pragma unroll
;                     for (int n = 0; n < 2; ++n) x[bj][n] = *(const f32x4*)(base + off + bj * HALF + 4 * n);
; #pragma unroll
;                 for (int bj = 0; bj < 2; ++bj) {
; #pragma unroll
;                     for (int n = 0; n < 2; ++n) { x[bj][n] = x[bj][n] + acc[ai][bj][m][n]; *(f32x4*)(out + off + bj * HALF + 4 * n) = x[bj][n];
;                         s += (x[bj][n][0] * x[bj][n][0] + x[bj][n][1] * x[bj][n][1]) + (x[bj][n][2] * x[bj][n][2] + x[bj][n][3] * x[bj][n][3]); }
;                     const f32x4 h0 = x[bj][0] * gv[bj][0], h1 = x[bj][1] * gv[bj][1];
;                     u32x4 w; w.x = cvt_pk_bf16(h0[0], h0[1]); w.y = cvt_pk_bf16(h0[2], h0[3]); w.z = cvt_pk_bf16(h1[0], h1[1]); w.w = cvt_pk_bf16(h1[2], h1[3]);
;                     *(u32x4*)(H + off + bj * HALF) = w; }
;                 s += __shfl_xor(s, 16); s += __shfl_xor(s, 32);
;                 if (fq == 0) atomicAdd(ss + row, s);
;                 if (m & 1) asm volatile("" ::: "memory"); }
.LBB0_852:
	s_or_b64 exec, exec, s[0:1]
	v_or_b32_e32 v112, 32, v162
	s_waitcnt lgkmcnt(0)
	v_ashrrev_i32_e32 v113, 31, v112
	v_lshlrev_b64 v[114:115], 11, v[112:113]
	v_lshl_add_u64 v[132:133], v[114:115], 0, v[160:161]
	v_lshlrev_b64 v[134:135], 2, v[132:133]
	v_lshl_add_u64 v[126:127], s[16:17], 0, v[134:135]
	global_load_dwordx4 v[114:117], v[126:127], off nt
	global_load_dwordx4 v[118:121], v[126:127], off offset:16 nt
	global_load_dwordx4 v[122:125], v[126:127], off offset:512 nt
	s_nop 0
	global_load_dwordx4 v[126:129], v[126:127], off offset:528 nt
	v_lshl_add_u64 v[134:135], s[8:9], 0, v[134:135]
	v_lshl_add_u64 v[132:133], v[132:133], 1, s[20:21]
	s_waitcnt vmcnt(3)
	v_pk_add_f32 v[110:111], v[110:111], v[116:117]
	v_pk_add_f32 v[108:109], v[108:109], v[114:115]
	s_waitcnt vmcnt(2)
	v_pk_add_f32 v[106:107], v[106:107], v[120:121]
	v_pk_add_f32 v[104:105], v[104:105], v[118:119]
	s_waitcnt vmcnt(1)
	v_pk_add_f32 v[102:103], v[102:103], v[124:125]
	v_pk_add_f32 v[100:101], v[100:101], v[122:123]
	v_mul_f32_e32 v122, v109, v109
	v_mul_f32_e32 v123, v111, v111
	v_mul_f32_e32 v124, v105, v105
	v_mul_f32_e32 v125, v107, v107
	s_waitcnt vmcnt(0)
	v_pk_add_f32 v[98:99], v[98:99], v[128:129]
	v_pk_add_f32 v[96:97], v[96:97], v[126:127]
	global_store_dwordx4 v[134:135], v[108:111], off nt
	v_pk_mul_f32 v[114:115], v[78:79], v[110:111]
	v_pk_mul_f32 v[116:117], v[76:77], v[108:109]
	v_mul_f32_e32 v109, v101, v101
	v_mul_f32_e32 v111, v103, v103
	v_fmac_f32_e32 v122, v108, v108
	v_fmac_f32_e32 v123, v110, v110
	v_fmac_f32_e32 v124, v104, v104
	v_fmac_f32_e32 v125, v106, v106
	global_store_dwordx4 v[134:135], v[104:107], off offset:16 nt
	v_pk_mul_f32 v[118:119], v[74:75], v[106:107]
	v_pk_mul_f32 v[120:121], v[72:73], v[104:105]
	v_mul_f32_e32 v126, v97, v97
	v_mul_f32_e32 v127, v99, v99
	v_cvt_pk_bf16_f32 v104, v116, v117
	v_cvt_pk_bf16_f32 v105, v114, v115
	v_cvt_pk_bf16_f32 v106, v120, v121
	v_cvt_pk_bf16_f32 v107, v118, v119
	v_fmac_f32_e32 v109, v100, v100
	v_fmac_f32_e32 v111, v102, v102
	v_add_f32_e32 v108, v122, v123
	v_add_f32_e32 v110, v124, v125
	v_fmac_f32_e32 v126, v96, v96
	v_fmac_f32_e32 v127, v98, v98
	global_store_dwordx4 v[132:133], v[104:107], off
	global_store_dwordx4 v[134:135], v[100:103], off offset:512 nt
	global_store_dwordx4 v[134:135], v[96:99], off offset:528 nt
	v_add_f32_e32 v104, v109, v111
	v_add_f32_e32 v106, v108, v110
	v_add_f32_e32 v105, v126, v127
	v_add_f32_e32 v104, v106, v104
	v_add_f32_e32 v108, v104, v105
	ds_bpermute_b32 v109, v171, v108
	v_pk_mul_f32 v[106:107], v[64:65], v[96:97]
	v_pk_mul_f32 v[100:101], v[68:69], v[100:101]
	v_pk_mul_f32 v[102:103], v[70:71], v[102:103]
	v_pk_mul_f32 v[104:105], v[66:67], v[98:99]
	s_waitcnt lgkmcnt(0)
	v_add_f32_e32 v96, v108, v109
	ds_bpermute_b32 v97, v130, v96
	v_cvt_pk_bf16_f32 v98, v100, v101
	v_cvt_pk_bf16_f32 v99, v102, v103
	v_cvt_pk_bf16_f32 v100, v106, v107
	v_cvt_pk_bf16_f32 v101, v104, v105
	global_store_dwordx4 v[132:133], v[98:101], off offset:256
	s_and_saveexec_b64 s[0:1], s[4:5]
	s_cbranch_execz .LBB0_854
	s_waitcnt lgkmcnt(0)
	v_add_f32_e32 v98, v96, v97
	v_lshl_add_u64 v[96:97], v[112:113], 2, s[10:11]
	global_atomic_add_f32 v[96:97], v98, off
.LBB0_854:
	s_or_b64 exec, exec, s[0:1]
	v_or_b32_e32 v96, 48, v162
	s_waitcnt lgkmcnt(0)
	v_ashrrev_i32_e32 v97, 31, v96
	v_lshlrev_b64 v[98:99], 11, v[96:97]
	v_lshl_add_u64 v[114:115], v[98:99], 0, v[160:161]
	v_lshlrev_b64 v[116:117], 2, v[114:115]
	v_lshl_add_u64 v[110:111], s[16:17], 0, v[116:117]
	global_load_dwordx4 v[98:101], v[110:111], off nt
	global_load_dwordx4 v[102:105], v[110:111], off offset:16 nt
	global_load_dwordx4 v[106:109], v[110:111], off offset:512 nt
	s_nop 0
	global_load_dwordx4 v[110:113], v[110:111], off offset:528 nt
	v_lshl_add_u64 v[116:117], s[8:9], 0, v[116:117]
	v_lshl_add_u64 v[114:115], v[114:115], 1, s[20:21]
	s_waitcnt vmcnt(3)
	v_pk_add_f32 v[94:95], v[94:95], v[100:101]
	v_pk_add_f32 v[92:93], v[92:93], v[98:99]
	s_waitcnt vmcnt(2)
	v_pk_add_f32 v[90:91], v[90:91], v[104:105]
	v_pk_add_f32 v[88:89], v[88:89], v[102:103]
	s_waitcnt vmcnt(1)
	v_pk_add_f32 v[86:87], v[86:87], v[108:109]
	v_pk_add_f32 v[84:85], v[84:85], v[106:107]
	v_mul_f32_e32 v106, v93, v93
	v_mul_f32_e32 v107, v95, v95
	v_mul_f32_e32 v108, v89, v89
	v_mul_f32_e32 v109, v91, v91
	s_waitcnt vmcnt(0)
	v_pk_add_f32 v[82:83], v[82:83], v[112:113]
	v_pk_add_f32 v[80:81], v[80:81], v[110:111]
	global_store_dwordx4 v[116:117], v[92:95], off nt
	v_pk_mul_f32 v[98:99], v[78:79], v[94:95]
	v_pk_mul_f32 v[100:101], v[76:77], v[92:93]
	v_mul_f32_e32 v93, v85, v85
	v_mul_f32_e32 v95, v87, v87
	v_fmac_f32_e32 v106, v92, v92
	v_fmac_f32_e32 v107, v94, v94
	v_fmac_f32_e32 v108, v88, v88
	v_fmac_f32_e32 v109, v90, v90
	global_store_dwordx4 v[116:117], v[88:91], off offset:16 nt
	v_pk_mul_f32 v[102:103], v[74:75], v[90:91]
	v_pk_mul_f32 v[104:105], v[72:73], v[88:89]
	v_mul_f32_e32 v110, v81, v81
	v_mul_f32_e32 v111, v83, v83
	v_cvt_pk_bf16_f32 v88, v100, v101
	v_cvt_pk_bf16_f32 v89, v98, v99
	v_cvt_pk_bf16_f32 v90, v104, v105
	v_cvt_pk_bf16_f32 v91, v102, v103
	v_fmac_f32_e32 v93, v84, v84
	v_fmac_f32_e32 v95, v86, v86
	v_add_f32_e32 v92, v106, v107
	v_add_f32_e32 v94, v108, v109
	v_fmac_f32_e32 v110, v80, v80
	v_fmac_f32_e32 v111, v82, v82
	global_store_dwordx4 v[114:115], v[88:91], off
	global_store_dwordx4 v[116:117], v[84:87], off offset:512 nt
	global_store_dwordx4 v[116:117], v[80:83], off offset:528 nt
	v_add_f32_e32 v88, v93, v95
	v_add_f32_e32 v90, v92, v94
	v_add_f32_e32 v89, v110, v111
	v_add_f32_e32 v88, v90, v88
	v_add_f32_e32 v92, v88, v89
	ds_bpermute_b32 v93, v171, v92
	v_pk_mul_f32 v[90:91], v[64:65], v[80:81]
	v_pk_mul_f32 v[84:85], v[68:69], v[84:85]
	v_pk_mul_f32 v[86:87], v[70:71], v[86:87]
	v_pk_mul_f32 v[88:89], v[66:67], v[82:83]
	s_waitcnt lgkmcnt(0)
	v_add_f32_e32 v80, v92, v93
	ds_bpermute_b32 v81, v130, v80
	v_cvt_pk_bf16_f32 v82, v84, v85
	v_cvt_pk_bf16_f32 v83, v86, v87
	v_cvt_pk_bf16_f32 v84, v90, v91
	v_cvt_pk_bf16_f32 v85, v88, v89
	global_store_dwordx4 v[114:115], v[82:85], off offset:256
	s_and_saveexec_b64 s[0:1], s[4:5]
	s_cbranch_execz .LBB0_856
	s_waitcnt lgkmcnt(0)
	v_add_f32_e32 v82, v80, v81
	v_lshl_add_u64 v[80:81], v[96:97], 2, s[10:11]
	global_atomic_add_f32 v[80:81], v82, off
; __device__ __forceinline__ unsigned cvt_pk_bf16(float lo, float hi) { unsigned r; asm volatile("v_cvt_pk_bf16_f32 %0, %1, %2" : "=v"(r) : "v"(lo), "v"(hi)); return r; }
;     __device__ __forceinline__ void operator()(const f32x4 (&acc)[2][2][4][2], const Unit& u, int wr, int wc, int fr, int fq) const {
;     ...
;             for (int m = 0; m < 4; ++m) { const int row = row0 + ai * HALF + m * 16; const size_t off = (size_t)row * ldc + col0;
;                 f32x4 x[2][2]; float s = 0.f;
; #pragma unroll
;                 for (int bj = 0; bj < 2; ++bj)
; #pragma unroll
;                     for (int n = 0; n < 2; ++n) x[bj][n] = *(const f32x4*)(base + off + bj * HALF + 4 * n);
; #pragma unroll
;                 for (int bj = 0; bj < 2; ++bj) {
; #pragma unroll
;                     for (int n = 0; n < 2; ++n) { x[bj][n] = x[bj][n] + acc[ai][bj][m][n]; *(f32x4*)(out + off + bj * HALF + 4 * n) = x[bj][n];
;                         s += (x[bj][n][0] * x[bj][n][0] + x[bj][n][1] * x[bj][n][1]) + (x[bj][n][2] * x[bj][n][2] + x[bj][n][3] * x[bj][n][3]); }
;                     const f32x4 h0 = x[bj][0] * gv[bj][0], h1 = x[bj][1] * gv[bj][1];
;                     u32x4 w; w.x = cvt_pk_bf16(h0[0], h0[1]); w.y = cvt_pk_bf16(h0[2], h0[3]); w.z = cvt_pk_bf16(h1[0], h1[1]); w.w = cvt_pk_bf16(h1[2], h1[3]);
;                     *(u32x4*)(H + off + bj * HALF) = w; }
;                 s += __shfl_xor(s, 16); s += __shfl_xor(s, 32);
;                 if (fq == 0) atomicAdd(ss + row, s);
;                 if (m & 1) asm volatile("" ::: "memory"); }
.LBB0_856:
	s_or_b64 exec, exec, s[0:1]
	v_add_u32_e32 v80, 0x80, v162
	s_waitcnt lgkmcnt(0)
	v_ashrrev_i32_e32 v81, 31, v80
	v_lshlrev_b64 v[82:83], 11, v[80:81]
	v_lshl_add_u64 v[98:99], v[82:83], 0, v[160:161]
	v_lshlrev_b64 v[100:101], 2, v[98:99]
	v_lshl_add_u64 v[94:95], s[16:17], 0, v[100:101]
	global_load_dwordx4 v[82:85], v[94:95], off nt
	global_load_dwordx4 v[86:89], v[94:95], off offset:16 nt
	global_load_dwordx4 v[90:93], v[94:95], off offset:512 nt
	s_nop 0
	global_load_dwordx4 v[94:97], v[94:95], off offset:528 nt
	v_lshl_add_u64 v[100:101], s[8:9], 0, v[100:101]
	v_lshl_add_u64 v[98:99], v[98:99], 1, s[20:21]
	s_waitcnt vmcnt(3)
	v_pk_add_f32 v[62:63], v[62:63], v[84:85]
	v_pk_add_f32 v[60:61], v[60:61], v[82:83]
	s_waitcnt vmcnt(2)
	v_pk_add_f32 v[58:59], v[58:59], v[88:89]
	v_pk_add_f32 v[56:57], v[56:57], v[86:87]
	s_waitcnt vmcnt(1)
	v_pk_add_f32 v[54:55], v[54:55], v[92:93]
	v_pk_add_f32 v[52:53], v[52:53], v[90:91]
	v_mul_f32_e32 v90, v61, v61
	v_mul_f32_e32 v91, v63, v63
	v_mul_f32_e32 v92, v57, v57
	v_mul_f32_e32 v93, v59, v59
	s_waitcnt vmcnt(0)
	v_pk_add_f32 v[50:51], v[50:51], v[96:97]
	v_pk_add_f32 v[48:49], v[48:49], v[94:95]
	global_store_dwordx4 v[100:101], v[60:63], off nt
	v_pk_mul_f32 v[82:83], v[78:79], v[62:63]
	v_pk_mul_f32 v[84:85], v[76:77], v[60:61]
	v_mul_f32_e32 v61, v53, v53
	v_mul_f32_e32 v63, v55, v55
	v_fmac_f32_e32 v90, v60, v60
	v_fmac_f32_e32 v91, v62, v62
	v_fmac_f32_e32 v92, v56, v56
	v_fmac_f32_e32 v93, v58, v58
	global_store_dwordx4 v[100:101], v[56:59], off offset:16 nt
	v_pk_mul_f32 v[86:87], v[74:75], v[58:59]
	v_pk_mul_f32 v[88:89], v[72:73], v[56:57]
	v_mul_f32_e32 v94, v49, v49
	v_mul_f32_e32 v95, v51, v51
	v_cvt_pk_bf16_f32 v56, v84, v85
	v_cvt_pk_bf16_f32 v57, v82, v83
	v_cvt_pk_bf16_f32 v58, v88, v89
	v_cvt_pk_bf16_f32 v59, v86, v87
	v_fmac_f32_e32 v61, v52, v52
	v_fmac_f32_e32 v63, v54, v54
	v_add_f32_e32 v60, v90, v91
	v_add_f32_e32 v62, v92, v93
	v_fmac_f32_e32 v94, v48, v48
	v_fmac_f32_e32 v95, v50, v50
	global_store_dwordx4 v[98:99], v[56:59], off
	global_store_dwordx4 v[100:101], v[52:55], off offset:512 nt
	global_store_dwordx4 v[100:101], v[48:51], off offset:528 nt
	v_add_f32_e32 v56, v61, v63
	v_add_f32_e32 v58, v60, v62
	v_add_f32_e32 v57, v94, v95
	v_add_f32_e32 v56, v58, v56
	v_add_f32_e32 v60, v56, v57
	ds_bpermute_b32 v61, v171, v60
	v_pk_mul_f32 v[58:59], v[64:65], v[48:49]
	v_pk_mul_f32 v[52:53], v[68:69], v[52:53]
	v_pk_mul_f32 v[54:55], v[70:71], v[54:55]
	v_pk_mul_f32 v[56:57], v[66:67], v[50:51]
	s_waitcnt lgkmcnt(0)
	v_add_f32_e32 v48, v60, v61
	ds_bpermute_b32 v49, v130, v48
	v_cvt_pk_bf16_f32 v50, v52, v53
	v_cvt_pk_bf16_f32 v51, v54, v55
	v_cvt_pk_bf16_f32 v52, v58, v59
	v_cvt_pk_bf16_f32 v53, v56, v57
	global_store_dwordx4 v[98:99], v[50:53], off offset:256
	s_and_saveexec_b64 s[0:1], s[4:5]
	s_cbranch_execz .LBB0_858
	s_waitcnt lgkmcnt(0)
	v_add_f32_e32 v50, v48, v49
	v_lshl_add_u64 v[48:49], v[80:81], 2, s[10:11]
	global_atomic_add_f32 v[48:49], v50, off
.LBB0_858:
	s_or_b64 exec, exec, s[0:1]
	v_add_u32_e32 v48, 0x90, v162
	s_waitcnt lgkmcnt(0)
	v_ashrrev_i32_e32 v49, 31, v48
	v_lshlrev_b64 v[50:51], 11, v[48:49]
	v_lshl_add_u64 v[62:63], v[50:51], 0, v[160:161]
	v_lshlrev_b64 v[84:85], 2, v[62:63]
	v_lshl_add_u64 v[80:81], s[16:17], 0, v[84:85]
	global_load_dwordx4 v[50:53], v[80:81], off nt
	global_load_dwordx4 v[54:57], v[80:81], off offset:16 nt
	global_load_dwordx4 v[58:61], v[80:81], off offset:512 nt
	s_nop 0
	global_load_dwordx4 v[80:83], v[80:81], off offset:528 nt
	v_lshl_add_u64 v[84:85], s[8:9], 0, v[84:85]
	v_lshl_add_u64 v[62:63], v[62:63], 1, s[20:21]
	s_waitcnt vmcnt(3)
	v_pk_add_f32 v[46:47], v[46:47], v[52:53]
	v_pk_add_f32 v[44:45], v[44:45], v[50:51]
	s_waitcnt vmcnt(2)
	v_pk_add_f32 v[42:43], v[42:43], v[56:57]
	v_pk_add_f32 v[40:41], v[40:41], v[54:55]
	s_waitcnt vmcnt(1)
	v_pk_add_f32 v[38:39], v[38:39], v[60:61]
	v_pk_add_f32 v[36:37], v[36:37], v[58:59]
	v_mul_f32_e32 v58, v45, v45
	v_mul_f32_e32 v59, v47, v47
	v_mul_f32_e32 v60, v41, v41
	v_mul_f32_e32 v61, v43, v43
	s_waitcnt vmcnt(0)
	v_pk_add_f32 v[34:35], v[34:35], v[82:83]
	v_pk_add_f32 v[32:33], v[32:33], v[80:81]
	global_store_dwordx4 v[84:85], v[44:47], off nt
	v_pk_mul_f32 v[50:51], v[78:79], v[46:47]
	v_pk_mul_f32 v[52:53], v[76:77], v[44:45]
	v_mul_f32_e32 v45, v37, v37
	v_mul_f32_e32 v47, v39, v39
	v_fmac_f32_e32 v58, v44, v44
	v_fmac_f32_e32 v59, v46, v46
	v_fmac_f32_e32 v60, v40, v40
	v_fmac_f32_e32 v61, v42, v42
	global_store_dwordx4 v[84:85], v[40:43], off offset:16 nt
	v_pk_mul_f32 v[54:55], v[74:75], v[42:43]
	v_pk_mul_f32 v[56:57], v[72:73], v[40:41]
	v_mul_f32_e32 v80, v33, v33
	v_mul_f32_e32 v81, v35, v35
	v_cvt_pk_bf16_f32 v40, v52, v53
	v_cvt_pk_bf16_f32 v41, v50, v51
	v_cvt_pk_bf16_f32 v42, v56, v57
	v_cvt_pk_bf16_f32 v43, v54, v55
	v_fmac_f32_e32 v45, v36, v36
	v_fmac_f32_e32 v47, v38, v38
	v_add_f32_e32 v44, v58, v59
	v_add_f32_e32 v46, v60, v61
	v_fmac_f32_e32 v80, v32, v32
	v_fmac_f32_e32 v81, v34, v34
	global_store_dwordx4 v[62:63], v[40:43], off
	global_store_dwordx4 v[84:85], v[36:39], off offset:512 nt
	global_store_dwordx4 v[84:85], v[32:35], off offset:528 nt
	v_add_f32_e32 v40, v45, v47
	v_add_f32_e32 v42, v44, v46
	v_add_f32_e32 v41, v80, v81
	v_add_f32_e32 v40, v42, v40
	v_add_f32_e32 v44, v40, v41
	ds_bpermute_b32 v45, v171, v44
	v_pk_mul_f32 v[42:43], v[64:65], v[32:33]
	v_pk_mul_f32 v[36:37], v[68:69], v[36:37]
	v_pk_mul_f32 v[38:39], v[70:71], v[38:39]
	v_pk_mul_f32 v[40:41], v[66:67], v[34:35]
	s_waitcnt lgkmcnt(0)
	v_add_f32_e32 v32, v44, v45
	ds_bpermute_b32 v33, v130, v32
	v_cvt_pk_bf16_f32 v34, v36, v37
	v_cvt_pk_bf16_f32 v35, v38, v39
	v_cvt_pk_bf16_f32 v36, v42, v43
	v_cvt_pk_bf16_f32 v37, v40, v41
	global_store_dwordx4 v[62:63], v[34:37], off offset:256
	s_and_saveexec_b64 s[0:1], s[4:5]
	s_cbranch_execz .LBB0_860
	s_waitcnt lgkmcnt(0)
	v_add_f32_e32 v34, v32, v33
	v_lshl_add_u64 v[32:33], v[48:49], 2, s[10:11]
	global_atomic_add_f32 v[32:33], v34, off
; __device__ __forceinline__ unsigned cvt_pk_bf16(float lo, float hi) { unsigned r; asm volatile("v_cvt_pk_bf16_f32 %0, %1, %2" : "=v"(r) : "v"(lo), "v"(hi)); return r; }
;     __device__ __forceinline__ void operator()(const f32x4 (&acc)[2][2][4][2], const Unit& u, int wr, int wc, int fr, int fq) const {
;     ...
;             for (int m = 0; m < 4; ++m) { const int row = row0 + ai * HALF + m * 16; const size_t off = (size_t)row * ldc + col0;
;                 f32x4 x[2][2]; float s = 0.f;
; #pragma unroll
;                 for (int bj = 0; bj < 2; ++bj)
; #pragma unroll
;                     for (int n = 0; n < 2; ++n) x[bj][n] = *(const f32x4*)(base + off + bj * HALF + 4 * n);
; #pragma unroll
;                 for (int bj = 0; bj < 2; ++bj) {
; #pragma unroll
;                     for (int n = 0; n < 2; ++n) { x[bj][n] = x[bj][n] + acc[ai][bj][m][n]; *(f32x4*)(out + off + bj * HALF + 4 * n) = x[bj][n];
;                         s += (x[bj][n][0] * x[bj][n][0] + x[bj][n][1] * x[bj][n][1]) + (x[bj][n][2] * x[bj][n][2] + x[bj][n][3] * x[bj][n][3]); }
;                     const f32x4 h0 = x[bj][0] * gv[bj][0], h1 = x[bj][1] * gv[bj][1];
;                     u32x4 w; w.x = cvt_pk_bf16(h0[0], h0[1]); w.y = cvt_pk_bf16(h0[2], h0[3]); w.z = cvt_pk_bf16(h1[0], h1[1]); w.w = cvt_pk_bf16(h1[2], h1[3]);
;                     *(u32x4*)(H + off + bj * HALF) = w; }
;                 s += __shfl_xor(s, 16); s += __shfl_xor(s, 32);
;                 if (fq == 0) atomicAdd(ss + row, s);
;                 if (m & 1) asm volatile("" ::: "memory"); }
.LBB0_860:
	s_or_b64 exec, exec, s[0:1]
	v_add_u32_e32 v32, 0xa0, v162
	s_waitcnt lgkmcnt(0)
	v_ashrrev_i32_e32 v33, 31, v32
	v_lshlrev_b64 v[34:35], 11, v[32:33]
	v_lshl_add_u64 v[50:51], v[34:35], 0, v[160:161]
	v_lshlrev_b64 v[52:53], 2, v[50:51]
	v_lshl_add_u64 v[46:47], s[16:17], 0, v[52:53]
	global_load_dwordx4 v[34:37], v[46:47], off nt
	global_load_dwordx4 v[38:41], v[46:47], off offset:16 nt
	global_load_dwordx4 v[42:45], v[46:47], off offset:512 nt
	s_nop 0
	global_load_dwordx4 v[46:49], v[46:47], off offset:528 nt
	v_lshl_add_u64 v[52:53], s[8:9], 0, v[52:53]
	v_lshl_add_u64 v[50:51], v[50:51], 1, s[20:21]
	s_waitcnt vmcnt(3)
	v_pk_add_f32 v[30:31], v[30:31], v[36:37]
	v_pk_add_f32 v[28:29], v[28:29], v[34:35]
	s_waitcnt vmcnt(2)
	v_pk_add_f32 v[26:27], v[26:27], v[40:41]
	v_pk_add_f32 v[24:25], v[24:25], v[38:39]
	s_waitcnt vmcnt(1)
	v_pk_add_f32 v[22:23], v[22:23], v[44:45]
	v_pk_add_f32 v[20:21], v[20:21], v[42:43]
	v_mul_f32_e32 v42, v29, v29
	v_mul_f32_e32 v43, v31, v31
	v_mul_f32_e32 v44, v25, v25
	v_mul_f32_e32 v45, v27, v27
	s_waitcnt vmcnt(0)
	v_pk_add_f32 v[18:19], v[18:19], v[48:49]
	v_pk_add_f32 v[16:17], v[16:17], v[46:47]
	global_store_dwordx4 v[52:53], v[28:31], off nt
	v_pk_mul_f32 v[34:35], v[78:79], v[30:31]
	v_pk_mul_f32 v[36:37], v[76:77], v[28:29]
	v_mul_f32_e32 v29, v21, v21
	v_mul_f32_e32 v31, v23, v23
	v_fmac_f32_e32 v42, v28, v28
	v_fmac_f32_e32 v43, v30, v30
	v_fmac_f32_e32 v44, v24, v24
	v_fmac_f32_e32 v45, v26, v26
	global_store_dwordx4 v[52:53], v[24:27], off offset:16 nt
	v_pk_mul_f32 v[38:39], v[74:75], v[26:27]
	v_pk_mul_f32 v[40:41], v[72:73], v[24:25]
	v_mul_f32_e32 v46, v17, v17
	v_mul_f32_e32 v47, v19, v19
	v_cvt_pk_bf16_f32 v24, v36, v37
	v_cvt_pk_bf16_f32 v25, v34, v35
	v_cvt_pk_bf16_f32 v26, v40, v41
	v_cvt_pk_bf16_f32 v27, v38, v39
	v_fmac_f32_e32 v29, v20, v20
	v_fmac_f32_e32 v31, v22, v22
	v_add_f32_e32 v28, v42, v43
	v_add_f32_e32 v30, v44, v45
	v_fmac_f32_e32 v46, v16, v16
	v_fmac_f32_e32 v47, v18, v18
	global_store_dwordx4 v[50:51], v[24:27], off
	global_store_dwordx4 v[52:53], v[20:23], off offset:512 nt
	global_store_dwordx4 v[52:53], v[16:19], off offset:528 nt
	v_add_f32_e32 v24, v29, v31
	v_add_f32_e32 v26, v28, v30
	v_add_f32_e32 v25, v46, v47
	v_add_f32_e32 v24, v26, v24
	v_add_f32_e32 v28, v24, v25
	ds_bpermute_b32 v29, v171, v28
	v_pk_mul_f32 v[26:27], v[64:65], v[16:17]
	v_pk_mul_f32 v[20:21], v[68:69], v[20:21]
	v_pk_mul_f32 v[22:23], v[70:71], v[22:23]
	v_pk_mul_f32 v[24:25], v[66:67], v[18:19]
	s_waitcnt lgkmcnt(0)
	v_add_f32_e32 v16, v28, v29
	ds_bpermute_b32 v17, v130, v16
	v_cvt_pk_bf16_f32 v18, v20, v21
	v_cvt_pk_bf16_f32 v19, v22, v23
	v_cvt_pk_bf16_f32 v20, v26, v27
	v_cvt_pk_bf16_f32 v21, v24, v25
	global_store_dwordx4 v[50:51], v[18:21], off offset:256
	s_and_saveexec_b64 s[0:1], s[4:5]
	s_cbranch_execz .LBB0_862
	s_waitcnt lgkmcnt(0)
	v_add_f32_e32 v18, v16, v17
	v_lshl_add_u64 v[16:17], v[32:33], 2, s[10:11]
	global_atomic_add_f32 v[16:17], v18, off
.LBB0_862:
	s_or_b64 exec, exec, s[0:1]
	v_add_u32_e32 v16, 0xb0, v162
	s_waitcnt lgkmcnt(0)
	v_ashrrev_i32_e32 v17, 31, v16
	v_lshlrev_b64 v[18:19], 11, v[16:17]
	v_lshl_add_u64 v[34:35], v[18:19], 0, v[160:161]
	v_lshlrev_b64 v[36:37], 2, v[34:35]
	v_lshl_add_u64 v[30:31], s[16:17], 0, v[36:37]
	global_load_dwordx4 v[18:21], v[30:31], off nt
	global_load_dwordx4 v[22:25], v[30:31], off offset:16 nt
	global_load_dwordx4 v[26:29], v[30:31], off offset:512 nt
	s_nop 0
	global_load_dwordx4 v[30:33], v[30:31], off offset:528 nt
	v_lshl_add_u64 v[36:37], s[8:9], 0, v[36:37]
	v_lshl_add_u64 v[34:35], v[34:35], 1, s[20:21]
	s_waitcnt vmcnt(3)
	v_pk_add_f32 v[14:15], v[14:15], v[20:21]
	v_pk_add_f32 v[12:13], v[12:13], v[18:19]
	s_waitcnt vmcnt(2)
	v_pk_add_f32 v[10:11], v[10:11], v[24:25]
	v_pk_add_f32 v[8:9], v[8:9], v[22:23]
	s_waitcnt vmcnt(1)
	v_pk_add_f32 v[6:7], v[6:7], v[28:29]
	v_pk_add_f32 v[4:5], v[4:5], v[26:27]
	v_mul_f32_e32 v26, v13, v13
	v_mul_f32_e32 v27, v15, v15
	v_mul_f32_e32 v28, v9, v9
	v_mul_f32_e32 v29, v11, v11
	s_waitcnt vmcnt(0)
	v_pk_add_f32 v[2:3], v[2:3], v[32:33]
	v_pk_add_f32 v[0:1], v[0:1], v[30:31]
	global_store_dwordx4 v[36:37], v[12:15], off nt
	v_pk_mul_f32 v[18:19], v[78:79], v[14:15]
	v_pk_mul_f32 v[20:21], v[76:77], v[12:13]
	v_mul_f32_e32 v13, v5, v5
	v_mul_f32_e32 v15, v7, v7
	v_fmac_f32_e32 v26, v12, v12
	v_fmac_f32_e32 v27, v14, v14
	v_fmac_f32_e32 v28, v8, v8
	v_fmac_f32_e32 v29, v10, v10
	global_store_dwordx4 v[36:37], v[8:11], off offset:16 nt
	v_pk_mul_f32 v[22:23], v[74:75], v[10:11]
	v_pk_mul_f32 v[24:25], v[72:73], v[8:9]
	v_mul_f32_e32 v30, v1, v1
	v_mul_f32_e32 v31, v3, v3
	v_cvt_pk_bf16_f32 v8, v20, v21
	v_cvt_pk_bf16_f32 v9, v18, v19
	v_cvt_pk_bf16_f32 v10, v24, v25
	v_cvt_pk_bf16_f32 v11, v22, v23
	v_fmac_f32_e32 v13, v4, v4
	v_fmac_f32_e32 v15, v6, v6
	v_add_f32_e32 v12, v26, v27
	v_add_f32_e32 v14, v28, v29
	v_fmac_f32_e32 v30, v0, v0
	v_fmac_f32_e32 v31, v2, v2
	global_store_dwordx4 v[34:35], v[8:11], off
	global_store_dwordx4 v[36:37], v[4:7], off offset:512 nt
	global_store_dwordx4 v[36:37], v[0:3], off offset:528 nt
	v_add_f32_e32 v8, v13, v15
	v_add_f32_e32 v10, v12, v14
	v_add_f32_e32 v9, v30, v31
	v_add_f32_e32 v8, v10, v8
	v_add_f32_e32 v12, v8, v9
	ds_bpermute_b32 v13, v171, v12
	v_pk_mul_f32 v[10:11], v[64:65], v[0:1]
	v_pk_mul_f32 v[4:5], v[68:69], v[4:5]
	v_pk_mul_f32 v[6:7], v[70:71], v[6:7]
	v_pk_mul_f32 v[8:9], v[66:67], v[2:3]
	s_waitcnt lgkmcnt(0)
	v_add_f32_e32 v0, v12, v13
	ds_bpermute_b32 v1, v130, v0
	v_cvt_pk_bf16_f32 v2, v4, v5
	v_cvt_pk_bf16_f32 v3, v6, v7
	v_cvt_pk_bf16_f32 v4, v10, v11
	v_cvt_pk_bf16_f32 v5, v8, v9
	global_store_dwordx4 v[34:35], v[2:5], off offset:256
	s_and_saveexec_b64 s[0:1], s[4:5]
	s_cbranch_execz .LBB0_864
	s_waitcnt lgkmcnt(0)
	v_add_f32_e32 v2, v0, v1
	v_lshl_add_u64 v[0:1], v[16:17], 2, s[10:11]
	global_atomic_add_f32 v[0:1], v2, off

;     __device__ __forceinline__ void operator()(const f32x4 (&acc)[2][2][4][2], const Unit& u, int wr, int wc, int fr, int fq) const {
;         const int row0 = u.pm * BM + wr * 64 + fr, col0 = u.pn * BM + wc * 32 + 4 * fq;
; #pragma unroll
;         for (int ai = 0; ai < 2; ++ai)
; #pragma unroll
;             for (int m = 0; m < 4; ++m) { const size_t off = (size_t)(row0 + ai * HALF + m * 16) * ldc + col0;
;                 f32x4 bs[2][2];
; #pragma unroll
;                 for (int bj = 0; bj < 2; ++bj)
; #pragma unroll
;                     for (int n = 0; n < 2; ++n) bs[bj][n] = *(const f32x4*)(base + off + bj * HALF + n * 16);
; #pragma unroll
;                 for (int bj = 0; bj < 2; ++bj)
; #pragma unroll
;                     for (int n = 0; n < 2; ++n) *(f32x4*)(out + off + bj * HALF + n * 16) = bs[bj][n] + acc[ai][bj][m][n];
;                 if (m & 1) asm volatile("" ::: "memory"); }
;     }
.LBB0_1093:
	v_lshl_add_u32 v180, s53, 8, v142
	v_lshl_or_b32 v140, s54, 8, v144
	v_ashrrev_i32_e32 v181, 31, v180
	v_ashrrev_i32_e32 v141, 31, v140
	v_lshlrev_b64 v[148:149], 13, v[180:181]
	v_or_b32_e32 v164, 16, v180
	v_lshl_add_u64 v[148:149], s[8:9], 0, v[148:149]
	v_lshlrev_b64 v[182:183], 2, v[140:141]
	v_ashrrev_i32_e32 v165, 31, v164
	v_lshl_add_u64 v[140:141], v[148:149], 0, v[182:183]
	v_lshlrev_b64 v[164:165], 13, v[164:165]
	global_load_dwordx4 v[148:151], v[140:141], off nt
	global_load_dwordx4 v[152:155], v[140:141], off offset:64 nt
	global_load_dwordx4 v[156:159], v[140:141], off offset:512 nt
	global_load_dwordx4 v[160:163], v[140:141], off offset:576 nt
	v_lshl_add_u64 v[164:165], s[8:9], 0, v[164:165]
	v_lshl_add_u64 v[184:185], v[164:165], 0, v[182:183]
	global_load_dwordx4 v[164:167], v[184:185], off nt
	global_load_dwordx4 v[168:171], v[184:185], off offset:64 nt
	global_load_dwordx4 v[172:175], v[184:185], off offset:512 nt
	global_load_dwordx4 v[176:179], v[184:185], off offset:576 nt
	v_or_b32_e32 v186, 32, v180
	v_or_b32_e32 v180, 48, v180
	v_ashrrev_i32_e32 v187, 31, v186
	v_lshlrev_b64 v[186:187], 13, v[186:187]
	v_ashrrev_i32_e32 v181, 31, v180
	v_lshl_add_u64 v[186:187], s[8:9], 0, v[186:187]
	v_lshl_add_u64 v[186:187], v[186:187], 0, v[182:183]
	s_waitcnt vmcnt(0)
	v_pk_add_f32 v[126:127], v[126:127], v[150:151]
	v_pk_add_f32 v[124:125], v[124:125], v[148:149]
	v_pk_add_f32 v[108:109], v[108:109], v[156:157]
	v_pk_add_f32 v[106:107], v[106:107], v[162:163]
	v_pk_add_f32 v[104:105], v[104:105], v[160:161]
	v_pk_add_f32 v[122:123], v[122:123], v[154:155]
	v_pk_add_f32 v[120:121], v[120:121], v[152:153]
	v_pk_add_f32 v[110:111], v[110:111], v[158:159]
	global_store_dwordx4 v[140:141], v[124:127], off nt
	global_store_dwordx4 v[140:141], v[120:123], off offset:64 nt
	global_store_dwordx4 v[140:141], v[108:111], off offset:512 nt
	global_store_dwordx4 v[140:141], v[104:107], off offset:576 nt
	v_pk_add_f32 v[102:103], v[102:103], v[174:175]
	v_pk_add_f32 v[108:109], v[112:113], v[168:169]
	v_pk_add_f32 v[106:107], v[118:119], v[166:167]
	v_pk_add_f32 v[104:105], v[116:117], v[164:165]
	v_pk_add_f32 v[110:111], v[114:115], v[170:171]
	v_pk_add_f32 v[100:101], v[100:101], v[172:173]
	v_pk_add_f32 v[98:99], v[98:99], v[178:179]
	v_pk_add_f32 v[96:97], v[96:97], v[176:177]
	global_store_dwordx4 v[184:185], v[104:107], off nt
	global_store_dwordx4 v[184:185], v[108:111], off offset:64 nt
	global_store_dwordx4 v[184:185], v[100:103], off offset:512 nt
	global_store_dwordx4 v[184:185], v[96:99], off offset:576 nt
	v_lshlrev_b64 v[108:109], 13, v[180:181]
	v_lshl_add_u64 v[112:113], s[8:9], 0, v[108:109]
	global_load_dwordx4 v[96:99], v[186:187], off nt
	global_load_dwordx4 v[100:103], v[186:187], off offset:64 nt
	v_lshl_add_u64 v[148:149], v[112:113], 0, v[182:183]
	global_load_dwordx4 v[104:107], v[186:187], off offset:512 nt
	global_load_dwordx4 v[108:111], v[186:187], off offset:576 nt
	global_load_dwordx4 v[112:115], v[148:149], off nt
	global_load_dwordx4 v[116:119], v[148:149], off offset:64 nt
	global_load_dwordx4 v[120:123], v[148:149], off offset:512 nt
	global_load_dwordx4 v[124:127], v[148:149], off offset:576 nt
	v_add_co_u32_e32 v152, vcc, s47, v140
	v_lshl_add_u64 v[150:151], v[140:141], 0, s[16:17]
	s_nop 0
	v_addc_co_u32_e32 v153, vcc, 0, v141, vcc
	s_waitcnt vmcnt(7)
	v_pk_add_f32 v[94:95], v[94:95], v[98:99]
	v_pk_add_f32 v[92:93], v[92:93], v[96:97]
	s_waitcnt vmcnt(6)
	v_pk_add_f32 v[90:91], v[90:91], v[102:103]
	v_pk_add_f32 v[88:89], v[88:89], v[100:101]
	s_waitcnt vmcnt(5)
	v_pk_add_f32 v[78:79], v[78:79], v[106:107]
	v_pk_add_f32 v[76:77], v[76:77], v[104:105]
	s_waitcnt vmcnt(4)
	v_pk_add_f32 v[74:75], v[74:75], v[110:111]
	v_pk_add_f32 v[72:73], v[72:73], v[108:109]
	s_waitcnt vmcnt(3)
	v_pk_add_f32 v[86:87], v[86:87], v[114:115]
	v_pk_add_f32 v[84:85], v[84:85], v[112:113]
	s_waitcnt vmcnt(2)
	v_pk_add_f32 v[82:83], v[82:83], v[118:119]
	v_pk_add_f32 v[80:81], v[80:81], v[116:117]
	s_waitcnt vmcnt(1)
	v_pk_add_f32 v[70:71], v[70:71], v[122:123]
	v_pk_add_f32 v[68:69], v[68:69], v[120:121]
	s_waitcnt vmcnt(0)
;     __device__ __forceinline__ void operator()(const f32x4 (&acc)[2][2][4][2], const Unit& u, int wr, int wc, int fr, int fq) const {
;         const int row0 = u.pm * BM + wr * 64 + fr, col0 = u.pn * BM + wc * 32 + 4 * fq;
; #pragma unroll
;         for (int ai = 0; ai < 2; ++ai)
; #pragma unroll
;             for (int m = 0; m < 4; ++m) { const size_t off = (size_t)(row0 + ai * HALF + m * 16) * ldc + col0;
;                 f32x4 bs[2][2];
; #pragma unroll
;                 for (int bj = 0; bj < 2; ++bj)
; #pragma unroll
;                     for (int n = 0; n < 2; ++n) bs[bj][n] = *(const f32x4*)(base + off + bj * HALF + n * 16);
; #pragma unroll
;                 for (int bj = 0; bj < 2; ++bj)
; #pragma unroll
;                     for (int n = 0; n < 2; ++n) *(f32x4*)(out + off + bj * HALF + n * 16) = bs[bj][n] + acc[ai][bj][m][n];
;                 if (m & 1) asm volatile("" ::: "memory"); }
;     }
	v_pk_add_f32 v[66:67], v[66:67], v[126:127]
	v_pk_add_f32 v[64:65], v[64:65], v[124:125]
	global_store_dwordx4 v[186:187], v[92:95], off nt
	global_store_dwordx4 v[186:187], v[88:91], off offset:64 nt
	global_store_dwordx4 v[186:187], v[76:79], off offset:512 nt
	global_store_dwordx4 v[186:187], v[72:75], off offset:576 nt
	global_store_dwordx4 v[148:149], v[84:87], off nt
	global_store_dwordx4 v[148:149], v[80:83], off offset:64 nt
	global_store_dwordx4 v[148:149], v[68:71], off offset:512 nt
	global_store_dwordx4 v[148:149], v[64:67], off offset:576 nt
	v_add_co_u32_e32 v96, vcc, s48, v140
	v_lshl_add_u64 v[98:99], v[140:141], 0, s[18:19]
	s_nop 0
	v_addc_co_u32_e32 v97, vcc, 0, v141, vcc
	global_load_dwordx4 v[64:67], v[152:153], off nt
	global_load_dwordx4 v[68:71], v[150:151], off offset:64 nt
	global_load_dwordx4 v[72:75], v[150:151], off offset:512 nt
	global_load_dwordx4 v[76:79], v[150:151], off offset:576 nt
	global_load_dwordx4 v[80:83], v[96:97], off nt
	global_load_dwordx4 v[84:87], v[98:99], off offset:64 nt
	global_load_dwordx4 v[88:91], v[98:99], off offset:512 nt
	global_load_dwordx4 v[92:95], v[98:99], off offset:576 nt
	v_add_co_u32_e32 v102, vcc, s49, v140
	v_lshl_add_u64 v[100:101], v[140:141], 0, s[20:21]
	s_nop 0
	v_addc_co_u32_e32 v103, vcc, 0, v141, vcc
	s_waitcnt vmcnt(7)
	v_pk_add_f32 v[62:63], v[62:63], v[66:67]
	v_pk_add_f32 v[60:61], v[60:61], v[64:65]
	s_waitcnt vmcnt(6)
	v_pk_add_f32 v[58:59], v[58:59], v[70:71]
	v_pk_add_f32 v[56:57], v[56:57], v[68:69]
	s_waitcnt vmcnt(5)
	v_pk_add_f32 v[46:47], v[46:47], v[74:75]
	v_pk_add_f32 v[44:45], v[44:45], v[72:73]
	s_waitcnt vmcnt(4)
	v_pk_add_f32 v[42:43], v[42:43], v[78:79]
	v_pk_add_f32 v[40:41], v[40:41], v[76:77]
	s_waitcnt vmcnt(3)
	v_pk_add_f32 v[54:55], v[54:55], v[82:83]
	v_pk_add_f32 v[52:53], v[52:53], v[80:81]
	s_waitcnt vmcnt(2)
	v_pk_add_f32 v[50:51], v[50:51], v[86:87]
	v_pk_add_f32 v[48:49], v[48:49], v[84:85]
	s_waitcnt vmcnt(1)
	v_pk_add_f32 v[38:39], v[38:39], v[90:91]
	v_pk_add_f32 v[36:37], v[36:37], v[88:89]
	s_waitcnt vmcnt(0)
	v_pk_add_f32 v[34:35], v[34:35], v[94:95]
	v_pk_add_f32 v[32:33], v[32:33], v[92:93]
	global_store_dwordx4 v[152:153], v[60:63], off nt
	global_store_dwordx4 v[150:151], v[56:59], off offset:64 nt
	global_store_dwordx4 v[150:151], v[44:47], off offset:512 nt
	global_store_dwordx4 v[150:151], v[40:43], off offset:576 nt
	global_store_dwordx4 v[96:97], v[52:55], off nt
	global_store_dwordx4 v[98:99], v[48:51], off offset:64 nt
	global_store_dwordx4 v[98:99], v[36:39], off offset:512 nt
	global_store_dwordx4 v[98:99], v[32:35], off offset:576 nt
	v_add_co_u32_e32 v64, vcc, s50, v140
	v_lshl_add_u64 v[66:67], v[140:141], 0, s[6:7]
	s_nop 0
	v_addc_co_u32_e32 v65, vcc, 0, v141, vcc
	global_load_dwordx4 v[32:35], v[102:103], off nt
	global_load_dwordx4 v[36:39], v[100:101], off offset:64 nt
	global_load_dwordx4 v[40:43], v[100:101], off offset:512 nt
	global_load_dwordx4 v[44:47], v[100:101], off offset:576 nt
	global_load_dwordx4 v[48:51], v[64:65], off nt
	global_load_dwordx4 v[52:55], v[66:67], off offset:64 nt
	global_load_dwordx4 v[56:59], v[66:67], off offset:512 nt
	global_load_dwordx4 v[60:63], v[66:67], off offset:576 nt
	s_and_b64 vcc, exec, s[0:1]
	s_mov_b64 s[0:1], -1
	s_waitcnt vmcnt(7)
	v_pk_add_f32 v[30:31], v[30:31], v[34:35]
	v_pk_add_f32 v[28:29], v[28:29], v[32:33]
	s_waitcnt vmcnt(6)
	v_pk_add_f32 v[26:27], v[26:27], v[38:39]
	v_pk_add_f32 v[24:25], v[24:25], v[36:37]
	s_waitcnt vmcnt(5)
	v_pk_add_f32 v[14:15], v[14:15], v[42:43]
	v_pk_add_f32 v[12:13], v[12:13], v[40:41]
	s_waitcnt vmcnt(4)
	v_pk_add_f32 v[10:11], v[10:11], v[46:47]
	v_pk_add_f32 v[8:9], v[8:9], v[44:45]
	s_waitcnt vmcnt(3)
	v_pk_add_f32 v[22:23], v[22:23], v[50:51]
	v_pk_add_f32 v[20:21], v[20:21], v[48:49]
	s_waitcnt vmcnt(2)
	v_pk_add_f32 v[18:19], v[18:19], v[54:55]
	v_pk_add_f32 v[16:17], v[16:17], v[52:53]
	s_waitcnt vmcnt(1)
	v_pk_add_f32 v[6:7], v[6:7], v[58:59]
	v_pk_add_f32 v[4:5], v[4:5], v[56:57]
	s_waitcnt vmcnt(0)
	v_pk_add_f32 v[2:3], v[2:3], v[62:63]
	v_pk_add_f32 v[0:1], v[0:1], v[60:61]
	global_store_dwordx4 v[102:103], v[28:31], off nt
	global_store_dwordx4 v[100:101], v[24:27], off offset:64 nt
	global_store_dwordx4 v[100:101], v[12:15], off offset:512 nt
	global_store_dwordx4 v[100:101], v[8:11], off offset:576 nt
	global_store_dwordx4 v[64:65], v[20:23], off nt
	global_store_dwordx4 v[66:67], v[16:19], off offset:64 nt
	global_store_dwordx4 v[66:67], v[4:7], off offset:512 nt
	global_store_dwordx4 v[66:67], v[0:3], off offset:576 nt
	s_cbranch_vccnz .LBB0_1078
	s_andn2_b64 vcc, exec, s[10:11]
	s_cbranch_vccnz .LBB0_1077
	s_barrier
	s_branch .LBB0_1077
